# v31 + deeper attention stagger: V reads VRD0-3 moved to QK gaps 4-6, waves 0-3 take the step barrier after QK MFMA 4 of the next step (7-gap skew)
# baseline (speedup 1.0000x reference)
; #define LAS __attribute__((address_space(3)))
; #define ATT_WAIT_BAR(N) asm volatile("s_waitcnt vmcnt(" #N ") lgkmcnt(0)\n\ts_barrier" ::: "memory")
; #define ATT_SB() __builtin_amdgcn_sched_barrier(0)
; #define ATT_PIN(x) asm volatile("" : "+v"(x))
; #define ATT_MFMA(a, b, c) __builtin_amdgcn_mfma_f32_32x32x16_bf16(a, b, c, 0, 0, 0)
; #define DMA_K(t, slot) glds16(ksrc + (long)(t) * KVBLK * DM, (unsigned)__builtin_amdgcn_readfirstlane(kdst + (slot) * KSLOT))
; #define DMA_V(t, slot) do { glds16(vsrc0 + (long)(t) * KVBLK * DM, (unsigned)__builtin_amdgcn_readfirstlane(vdst + (slot) * VSLOT)); \
;         glds16(vsrc0 + (long)(t) * KVBLK * DM + 1024, (unsigned)__builtin_amdgcn_readfirstlane(vdst + (slot) * VSLOT + 8192)); } while (0)
; #define ROT() do { sl_prev = sl_cur; sl_cur = sl_next; sl_next = (sl_next == 2) ? 0 : sl_next + 1; } while (0)
; __device__ __forceinline__ void attn_unit(int b, int h, int qb, bool first, bool has_next, int nb, int nh, bf16_t* QO, const bf16_t* __restrict__ K, const bf16_t* __restrict__ V, float lam, char* shm) {
;     ...
;         for (int d0 = 0; d0 < 4; ++d0) o[d0] = f32x16{};
;         f32x16 pA0, pA1, pB0, pB1; bf16x8 kf[8]; s16x4 vlo[4], vhi[4]; u32x4 pw0, pw1, pw2, pw3;
;         int sl_prev = 0, sl_cur = 0, sl_next = 1;
;     ...
;         ATT_WAIT_BAR(4);
;         { const lds_cptr kp = kp0; pA0 = f32x16{}; pA1 = f32x16{};
; #pragma unroll
;           for (int d0 = 0; d0 < 4; ++d0) { const bf16x8 k0 = *(const LAS bf16x8*)(kp + d0 * 2048), k1 = *(const LAS bf16x8*)(kp + d0 * 2048 + 512);
;               pA0 = ATT_MFMA(k0, qr[d0], pA0); pA1 = ATT_MFMA(k1, qr[d0], pA1); }
; #pragma unroll
;           for (int r = 0; r < 16; ++r) { pA0[r] = __builtin_amdgcn_exp2f(pA0[r]); pA1[r] = __builtin_amdgcn_exp2f(pA1[r]); }
;           ATT_PIN(pA0); ATT_PIN(pA1); }
;         ATT_SB();
;         ATT_WAIT_BAR(0);
;         DMA_K(3, 0); DMA_V(1, 1);
;         ROT();
; #pragma unroll
;         for (int j = 0; j < 4; ++j) kload2(kf, kp0 + sl_cur * KSLOT, j);
;         ATT_WAIT_BAR(3);
.LBB0_374:
	s_waitcnt vmcnt(4) lgkmcnt(0)
	s_barrier
	ds_read_b128 v[2:5], v243
	ds_read_b128 v[18:21], v243 offset:512
	ds_read_b128 v[34:37], v243 offset:2048
	ds_read_b128 v[38:41], v243 offset:2560
	s_xor_b64 s[52:53], s[54:55], -1
	s_mov_b32 s60, 0
	s_waitcnt vmcnt(3) lgkmcnt(3)
	v_mfma_f32_32x32x16_bf16 v[2:17], v[2:5], v[190:193], 0
	s_waitcnt lgkmcnt(2)
	v_mfma_f32_32x32x16_bf16 v[18:33], v[18:21], v[190:193], 0
	s_waitcnt vmcnt(2) lgkmcnt(1)
	v_mfma_f32_32x32x16_bf16 v[2:17], v[34:37], v[186:189], v[2:17]
	s_waitcnt lgkmcnt(0)
	v_mfma_f32_32x32x16_bf16 v[18:33], v[38:41], v[186:189], v[18:33]
	ds_read_b128 v[34:37], v243 offset:4096
	ds_read_b128 v[38:41], v243 offset:4608
	s_waitcnt vmcnt(1) lgkmcnt(1)
	v_mfma_f32_32x32x16_bf16 v[2:17], v[34:37], v[182:185], v[2:17]
	s_waitcnt lgkmcnt(0)
	v_mfma_f32_32x32x16_bf16 v[18:33], v[38:41], v[182:185], v[18:33]
	ds_read_b128 v[34:37], v243 offset:6144
	ds_read_b128 v[38:41], v243 offset:6656
	s_waitcnt vmcnt(0) lgkmcnt(1)
	v_mfma_f32_32x32x16_bf16 v[2:17], v[34:37], v[178:181], v[2:17]
	s_waitcnt lgkmcnt(0)
	v_mfma_f32_32x32x16_bf16 v[18:33], v[38:41], v[178:181], v[18:33]
	s_nop 9
	v_exp_f32_e32 v82, v2
	v_exp_f32_e32 v83, v3
	v_exp_f32_e32 v84, v4
	v_exp_f32_e32 v85, v5
	v_exp_f32_e32 v86, v6
	v_exp_f32_e32 v87, v7
	v_exp_f32_e32 v88, v8
	v_exp_f32_e32 v66, v18
	v_exp_f32_e32 v67, v19
	v_exp_f32_e32 v68, v20
	v_exp_f32_e32 v69, v21
	v_exp_f32_e32 v70, v22
	v_exp_f32_e32 v71, v23
	v_exp_f32_e32 v72, v24
	v_exp_f32_e32 v89, v9
	v_exp_f32_e32 v73, v25
	v_exp_f32_e32 v90, v10
	v_exp_f32_e32 v74, v26
	v_exp_f32_e32 v91, v11
	v_exp_f32_e32 v75, v27
	v_exp_f32_e32 v92, v12
	v_exp_f32_e32 v76, v28
	v_exp_f32_e32 v93, v13
	v_exp_f32_e32 v77, v29
	v_exp_f32_e32 v94, v14
	v_exp_f32_e32 v78, v30
	v_exp_f32_e32 v95, v15
	v_exp_f32_e32 v79, v31
	v_exp_f32_e32 v96, v16
	v_exp_f32_e32 v80, v32
	v_exp_f32_e32 v97, v17
	v_exp_f32_e32 v81, v33
	s_waitcnt vmcnt(0) lgkmcnt(0)
	s_barrier
	v_lshl_add_u64 v[2:3], v[232:233], 0, s[24:25]
	s_mov_b32 s0, m0
	s_mov_b32 m0, s91
	s_nop 0
	global_load_lds_dwordx4 v[2:3], off
	s_mov_b32 m0, s0
	s_cmp_lg_u32 0, -1
	s_cselect_b32 s0, 0, 0
	s_add_i32 s0, s0, s90
	s_add_i32 s12, s0, 0xa000
	s_mov_b32 s13, m0
	s_mov_b32 m0, s12
	s_nop 0
	global_load_lds_dwordx4 v[210:211], off
	s_mov_b32 m0, s13
	s_add_i32 s0, s0, 0xc000
	s_mov_b32 s12, m0
	s_mov_b32 m0, s0
	s_nop 0
	global_load_lds_dwordx4 v[212:213], off
	s_mov_b32 m0, s12
	ds_read_b128 v[102:105], v243 offset:8192
	ds_read_b128 v[98:101], v243 offset:8704
	ds_read_b128 v[198:201], v243 offset:10240
	ds_read_b128 v[142:145], v243 offset:10752
	ds_read_b128 v[194:197], v243 offset:12288
	ds_read_b128 v[134:137], v243 offset:12800
	ds_read_b128 v[138:141], v243 offset:14336
	ds_read_b128 v[130:133], v243 offset:14848
	s_waitcnt vmcnt(3) lgkmcnt(0)
	s_cmp_lg_u32 s98, 0
	s_cbranch_scc0 .Lds_p0
	s_barrier
.Lds_p0:
	s_add_i32 s0, s81, s7
	v_mov_b32_e32 v202, 0
	s_mov_b32 s6, -1
	s_mov_b32 s7, 1
	v_lshl_add_u64 v[146:147], s[0:1], 1, v[228:229]
	s_mov_b32 s0, 2
	v_mov_b64_e32 v[148:149], v[230:231]
	v_mov_b32_e32 v50, 0
	v_mov_b32_e32 v51, v202
	v_mov_b32_e32 v52, v202
	v_mov_b32_e32 v53, v202
	v_mov_b32_e32 v54, v202
	v_mov_b32_e32 v55, v202
	v_mov_b32_e32 v56, v202
	v_mov_b32_e32 v57, v202
	v_mov_b32_e32 v58, v202
	v_mov_b32_e32 v59, v202
	v_mov_b32_e32 v60, v202
	v_mov_b32_e32 v61, v202
	v_mov_b32_e32 v62, v202
	v_mov_b32_e32 v63, v202
	v_mov_b32_e32 v64, v202
	v_mov_b32_e32 v65, v202
	v_mov_b32_e32 v34, 0
	v_mov_b32_e32 v35, v202
	v_mov_b32_e32 v36, v202
	v_mov_b32_e32 v37, v202
	v_mov_b32_e32 v38, v202
	v_mov_b32_e32 v39, v202
	v_mov_b32_e32 v40, v202
	v_mov_b32_e32 v41, v202
	v_mov_b32_e32 v42, v202
	v_mov_b32_e32 v43, v202
	v_mov_b32_e32 v44, v202
	v_mov_b32_e32 v45, v202
	v_mov_b32_e32 v46, v202
	v_mov_b32_e32 v47, v202
	v_mov_b32_e32 v48, v202
	v_mov_b32_e32 v49, v202
	v_mov_b32_e32 v18, 0
	v_mov_b32_e32 v19, v202
	v_mov_b32_e32 v20, v202
	v_mov_b32_e32 v21, v202
	v_mov_b32_e32 v22, v202
	v_mov_b32_e32 v23, v202
	v_mov_b32_e32 v24, v202
	v_mov_b32_e32 v25, v202
	v_mov_b32_e32 v26, v202
	v_mov_b32_e32 v27, v202
	v_mov_b32_e32 v28, v202
	v_mov_b32_e32 v29, v202
	v_mov_b32_e32 v30, v202
	v_mov_b32_e32 v31, v202
	v_mov_b32_e32 v32, v202
	v_mov_b32_e32 v33, v202
	v_mov_b32_e32 v2, 0
	v_mov_b32_e32 v3, v202
	v_mov_b32_e32 v4, v202
	v_mov_b32_e32 v5, v202
	v_mov_b32_e32 v6, v202
	v_mov_b32_e32 v7, v202
	v_mov_b32_e32 v8, v202
	v_mov_b32_e32 v9, v202
	v_mov_b32_e32 v10, v202
	v_mov_b32_e32 v11, v202
	v_mov_b32_e32 v12, v202
	v_mov_b32_e32 v13, v202
	v_mov_b32_e32 v14, v202
	v_mov_b32_e32 v15, v202
	v_mov_b32_e32 v16, v202
	v_mov_b32_e32 v17, v202
.LBB0_375:
	v_lshl_add_u32 v154, s60, 14, v241
	v_add_f32_e32 v106, v82, v83
	v_add_f32_e32 v106, v84, v106
	v_add_f32_e32 v106, v85, v106
	v_add_f32_e32 v106, v86, v106
	v_add_f32_e32 v106, v87, v106
	v_cvt_pk_bf16_f32 v174, v82, v83
	v_cvt_pk_bf16_f32 v175, v84, v85
	s_waitcnt lgkmcnt(9)
	v_mfma_f32_32x32x16_bf16 v[114:129], v[102:105], v[190:193], 0
	v_add_f32_e32 v102, v88, v106
	v_add_f32_e32 v102, v89, v102
	v_add_f32_e32 v102, v90, v102
	v_add_f32_e32 v155, v91, v102
	s_waitcnt lgkmcnt(10)
	v_mfma_f32_32x32x16_bf16 v[98:113], v[98:101], v[190:193], 0
	v_cvt_pk_bf16_f32 v176, v86, v87
	v_cvt_pk_bf16_f32 v177, v88, v89
	v_add_f32_e32 v155, v92, v155
	v_add_f32_e32 v155, v93, v155
	v_add_f32_e32 v155, v94, v155
	v_add_f32_e32 v155, v95, v155
	v_cvt_pk_bf16_f32 v170, v90, v91
	v_cvt_pk_bf16_f32 v171, v92, v93
	s_waitcnt lgkmcnt(11)
	v_mfma_f32_32x32x16_bf16 v[114:129], v[198:201], v[186:189], v[114:129]
	s_waitcnt lgkmcnt(12)
	v_mfma_f32_32x32x16_bf16 v[98:113], v[142:145], v[186:189], v[98:113]
	v_add_f32_e32 v155, v96, v155
	v_add_f32_e32 v155, v97, v155
	v_add_f32_e32 v155, v66, v155
	v_add_f32_e32 v155, v67, v155
	v_cvt_pk_bf16_f32 v172, v94, v95
	v_cvt_pk_bf16_f32 v173, v96, v97
	s_nop 0
	v_add_f32_e32 v94, v68, v155
	v_add_f32_e32 v94, v69, v94
	v_add_f32_e32 v94, v70, v94
	v_add_f32_e32 v94, v71, v94
	v_cvt_pk_bf16_f32 v166, v66, v67
	v_cvt_pk_bf16_f32 v167, v68, v69
	s_cmp_lg_u32 s98, 0
	s_cbranch_scc1 .Lds_a0
	s_waitcnt vmcnt(3) lgkmcnt(0)
	s_barrier
.Lds_a0:
	ds_read_b64_tr_b16 v[150:151], v154 offset:24576
	ds_read_b64_tr_b16 v[152:153], v154 offset:25088
	ds_read_b64_tr_b16 v[82:83], v154 offset:28672
	ds_read_b64_tr_b16 v[84:85], v154 offset:29184
	s_waitcnt lgkmcnt(11)
	v_mfma_f32_32x32x16_bf16 v[114:129], v[194:197], v[182:185], v[114:129]
	ds_read_b64_tr_b16 v[86:87], v154 offset:32768
	ds_read_b64_tr_b16 v[88:89], v154 offset:33280
	s_waitcnt lgkmcnt(10)
	v_mfma_f32_32x32x16_bf16 v[98:113], v[134:137], v[182:185], v[98:113]
	v_add_f32_e32 v66, v72, v94
	v_add_f32_e32 v66, v73, v66
	v_add_f32_e32 v66, v74, v66
	v_add_f32_e32 v66, v75, v66
	v_cvt_pk_bf16_f32 v168, v70, v71
	v_cvt_pk_bf16_f32 v169, v72, v73
	s_nop 0
	v_add_f32_e32 v66, v76, v66
	v_add_f32_e32 v66, v77, v66
	v_add_f32_e32 v66, v78, v66
	v_add_f32_e32 v66, v79, v66
	v_cvt_pk_bf16_f32 v162, v74, v75
	v_cvt_pk_bf16_f32 v163, v76, v77
	ds_read_b64_tr_b16 v[90:91], v154 offset:36864
	ds_read_b64_tr_b16 v[92:93], v154 offset:37376
	s_waitcnt lgkmcnt(9)
	v_mfma_f32_32x32x16_bf16 v[114:129], v[138:141], v[178:181], v[114:129]
	s_waitcnt lgkmcnt(8)
	v_mfma_f32_32x32x16_bf16 v[98:113], v[130:133], v[178:181], v[98:113]
	v_add_f32_e32 v66, v80, v66
	v_add_f32_e32 v66, v81, v66
	v_add_f32_e32 v66, 0, v66
	v_cvt_pk_bf16_f32 v164, v78, v79
	v_cvt_pk_bf16_f32 v165, v80, v81
	s_lshl_b32 s12, s7, 13
	s_add_i32 s12, s12, s91
	v_add_f32_e32 v198, v202, v66
	v_lshl_add_u64 v[66:67], v[146:147], 0, s[24:25]
	s_mov_b32 s13, m0
	s_mov_b32 m0, s12
	s_nop 0
	global_load_lds_dwordx4 v[66:67], off
	s_mov_b32 m0, s13
	s_lshl_b32 s12, s0, 14
	v_lshl_add_u64 v[66:67], v[148:149], 0, s[4:5]
	s_add_i32 s12, s12, s92
	s_mov_b32 s13, m0
	s_mov_b32 m0, s12
	s_nop 0
	global_load_lds_dwordx4 v[66:67], off
	s_mov_b32 m0, s13
	v_lshl_add_u64 v[66:67], v[148:149], 0, s[8:9]
	s_addk_i32 s12, 0x2000
	s_mov_b32 s13, m0
	s_mov_b32 m0, s12
	s_nop 0
	global_load_lds_dwordx4 v[66:67], off
	s_mov_b32 m0, s13
	s_waitcnt lgkmcnt(6)
	v_mfma_f32_32x32x16_bf16 v[50:65], v[174:177], v[150:153], v[50:65]
	v_exp_f32_e32 v114, v114
	v_exp_f32_e32 v115, v115
	ds_read_b64_tr_b16 v[66:67], v154 offset:25600
	ds_read_b64_tr_b16 v[68:69], v154 offset:26112
	s_waitcnt lgkmcnt(6)
	v_mfma_f32_32x32x16_bf16 v[34:49], v[174:177], v[82:85], v[34:49]
	v_exp_f32_e32 v116, v116
	v_exp_f32_e32 v117, v117
	ds_read_b64_tr_b16 v[70:71], v154 offset:29696
	ds_read_b64_tr_b16 v[72:73], v154 offset:30208
	s_waitcnt lgkmcnt(6)
	v_mfma_f32_32x32x16_bf16 v[18:33], v[174:177], v[86:89], v[18:33]
	v_exp_f32_e32 v118, v118
	v_exp_f32_e32 v119, v119
	ds_read_b64_tr_b16 v[74:75], v154 offset:33792
	ds_read_b64_tr_b16 v[76:77], v154 offset:34304
	s_waitcnt lgkmcnt(6)
	v_mfma_f32_32x32x16_bf16 v[2:17], v[174:177], v[90:93], v[2:17]
	v_exp_f32_e32 v120, v120
	v_exp_f32_e32 v121, v121
	ds_read_b64_tr_b16 v[78:79], v154 offset:37888
	ds_read_b64_tr_b16 v[80:81], v154 offset:38400
	s_waitcnt lgkmcnt(6)
	v_mfma_f32_32x32x16_bf16 v[50:65], v[170:173], v[66:69], v[50:65]
	v_exp_f32_e32 v122, v122
	v_exp_f32_e32 v123, v123
	ds_read_b64_tr_b16 v[82:83], v154 offset:26624
	ds_read_b64_tr_b16 v[84:85], v154 offset:27136
	s_waitcnt lgkmcnt(6)
	v_mfma_f32_32x32x16_bf16 v[34:49], v[170:173], v[70:73], v[34:49]
	v_exp_f32_e32 v124, v124
	v_exp_f32_e32 v125, v125
	ds_read_b64_tr_b16 v[66:67], v154 offset:30720
	ds_read_b64_tr_b16 v[68:69], v154 offset:31232
	s_waitcnt lgkmcnt(6)
	v_mfma_f32_32x32x16_bf16 v[18:33], v[170:173], v[74:77], v[18:33]
	s_lshl_b32 s60, s0, 13
	v_exp_f32_e32 v126, v126
	v_exp_f32_e32 v127, v127
	v_add_u32_e32 v90, s60, v243
	ds_read_b128 v[70:73], v90
	ds_read_b128 v[130:133], v90 offset:512
	ds_read_b64_tr_b16 v[86:87], v154 offset:34816
	ds_read_b64_tr_b16 v[88:89], v154 offset:35328
	s_waitcnt lgkmcnt(8)
	v_mfma_f32_32x32x16_bf16 v[2:17], v[170:173], v[78:81], v[2:17]
	v_exp_f32_e32 v128, v128
	v_exp_f32_e32 v129, v129
	ds_read_b64_tr_b16 v[74:75], v154 offset:38912
	ds_read_b64_tr_b16 v[76:77], v154 offset:39424
	s_waitcnt lgkmcnt(8)
	v_mfma_f32_32x32x16_bf16 v[50:65], v[166:169], v[82:85], v[50:65]
	v_exp_f32_e32 v98, v98
	v_exp_f32_e32 v99, v99
	ds_read_b128 v[134:137], v90 offset:2048
	ds_read_b128 v[138:141], v90 offset:2560
	ds_read_b64_tr_b16 v[78:79], v154 offset:27648
	ds_read_b64_tr_b16 v[80:81], v154 offset:28160
	s_waitcnt lgkmcnt(10)
	v_mfma_f32_32x32x16_bf16 v[34:49], v[166:169], v[66:69], v[34:49]
	v_exp_f32_e32 v100, v100
	v_exp_f32_e32 v101, v101
	ds_read_b64_tr_b16 v[82:83], v154 offset:31744
	ds_read_b64_tr_b16 v[84:85], v154 offset:32256
	s_waitcnt lgkmcnt(8)
	v_mfma_f32_32x32x16_bf16 v[18:33], v[166:169], v[86:89], v[18:33]
	v_exp_f32_e32 v102, v102
	v_exp_f32_e32 v103, v103
	ds_read_b128 v[142:145], v90 offset:4096
	ds_read_b128 v[150:153], v90 offset:4608
	ds_read_b64_tr_b16 v[66:67], v154 offset:35840
	ds_read_b64_tr_b16 v[68:69], v154 offset:36352
	s_waitcnt lgkmcnt(10)
	v_mfma_f32_32x32x16_bf16 v[2:17], v[166:169], v[74:77], v[2:17]
	v_exp_f32_e32 v104, v104
	v_exp_f32_e32 v105, v105
	ds_read_b64_tr_b16 v[86:87], v154 offset:39936
	ds_read_b64_tr_b16 v[88:89], v154 offset:40448
	s_waitcnt lgkmcnt(8)
	v_mfma_f32_32x32x16_bf16 v[50:65], v[162:165], v[78:81], v[50:65]
	ds_read_b128 v[154:157], v90 offset:6144
	ds_read_b128 v[158:161], v90 offset:6656
	v_exp_f32_e32 v106, v106
	v_exp_f32_e32 v107, v107
	s_cmp_lg_u32 s98, 0
	s_cbranch_scc0 .Lst_e0
	s_waitcnt vmcnt(3) lgkmcnt(0)
	s_barrier
.Lst_e0:
	s_waitcnt lgkmcnt(8)
	v_mfma_f32_32x32x16_bf16 v[34:49], v[162:165], v[82:85], v[34:49]
	v_exp_f32_e32 v108, v108
	v_exp_f32_e32 v109, v109
	s_waitcnt lgkmcnt(4)
	v_mfma_f32_32x32x16_bf16 v[18:33], v[162:165], v[66:69], v[18:33]
	v_exp_f32_e32 v110, v110
	v_exp_f32_e32 v111, v111
	s_waitcnt lgkmcnt(2)
	v_mfma_f32_32x32x16_bf16 v[2:17], v[162:165], v[86:89], v[2:17]
	v_exp_f32_e32 v112, v112
	v_exp_f32_e32 v113, v113
	s_waitcnt lgkmcnt(0)
	s_add_i32 s12, s0, 1
	s_cmp_lg_u32 s0, 2
	s_cselect_b32 s33, s12, 0
	v_lshl_add_u32 v244, s7, 14, v241
	v_mfma_f32_32x32x16_bf16 v[82:97], v[70:73], v[190:193], 0
	v_add_f32_e32 v66, v114, v115
	v_add_f32_e32 v66, v116, v66
	v_add_f32_e32 v66, v117, v66
	v_add_f32_e32 v66, v118, v66
	v_add_f32_e32 v66, v119, v66
	v_cvt_pk_bf16_f32 v174, v114, v115
	v_cvt_pk_bf16_f32 v175, v116, v117
	v_add_f32_e32 v66, v120, v66
	v_add_f32_e32 v66, v121, v66
	v_add_f32_e32 v66, v122, v66
	v_add_f32_e32 v162, v123, v66
	v_mfma_f32_32x32x16_bf16 v[66:81], v[130:133], v[190:193], 0
	v_cvt_pk_bf16_f32 v176, v118, v119
	v_cvt_pk_bf16_f32 v177, v120, v121
	v_mfma_f32_32x32x16_bf16 v[82:97], v[134:137], v[186:189], v[82:97]
	v_add_f32_e32 v130, v124, v162
	v_add_f32_e32 v130, v125, v130
	v_add_f32_e32 v130, v126, v130
	v_add_f32_e32 v130, v127, v130
	v_cvt_pk_bf16_f32 v170, v122, v123
	v_cvt_pk_bf16_f32 v171, v124, v125
	v_mfma_f32_32x32x16_bf16 v[66:81], v[138:141], v[186:189], v[66:81]
	v_add_f32_e32 v130, v128, v130
	v_add_f32_e32 v130, v129, v130
	v_add_f32_e32 v130, v98, v130
	v_add_f32_e32 v130, v99, v130
	v_cvt_pk_bf16_f32 v172, v126, v127
	v_cvt_pk_bf16_f32 v173, v128, v129
	s_cmp_lg_u32 s98, 0
	s_cbranch_scc1 .Lds_a1
	s_waitcnt vmcnt(3) lgkmcnt(0)
	s_barrier
.Lds_a1:
	ds_read_b64_tr_b16 v[194:195], v244 offset:24576
	ds_read_b64_tr_b16 v[196:197], v244 offset:25088
	ds_read_b64_tr_b16 v[114:115], v244 offset:28672
	ds_read_b64_tr_b16 v[116:117], v244 offset:29184
	v_mfma_f32_32x32x16_bf16 v[82:97], v[142:145], v[182:185], v[82:97]
	v_add_f32_e32 v126, v100, v130
	v_add_f32_e32 v126, v101, v126
	v_add_f32_e32 v126, v102, v126
	v_add_f32_e32 v126, v103, v126
	v_cvt_pk_bf16_f32 v166, v98, v99
	v_cvt_pk_bf16_f32 v167, v100, v101
	ds_read_b64_tr_b16 v[118:119], v244 offset:32768
	ds_read_b64_tr_b16 v[120:121], v244 offset:33280
	v_mfma_f32_32x32x16_bf16 v[66:81], v[150:153], v[182:185], v[66:81]
	v_add_f32_e32 v98, v104, v126
	v_add_f32_e32 v98, v105, v98
	v_add_f32_e32 v98, v106, v98
	v_add_f32_e32 v98, v107, v98
	v_cvt_pk_bf16_f32 v168, v102, v103
	v_cvt_pk_bf16_f32 v169, v104, v105
	ds_read_b64_tr_b16 v[122:123], v244 offset:36864
	ds_read_b64_tr_b16 v[124:125], v244 offset:37376
	s_waitcnt lgkmcnt(9)
	v_mfma_f32_32x32x16_bf16 v[82:97], v[154:157], v[178:181], v[82:97]
	v_add_f32_e32 v98, v108, v98
	v_add_f32_e32 v98, v109, v98
	v_add_f32_e32 v98, v110, v98
	v_add_f32_e32 v98, v111, v98
	v_cvt_pk_bf16_f32 v162, v106, v107
	v_cvt_pk_bf16_f32 v163, v108, v109
	s_waitcnt lgkmcnt(8)
	v_mfma_f32_32x32x16_bf16 v[66:81], v[158:161], v[178:181], v[66:81]
	v_add_f32_e32 v98, v112, v98
	v_add_f32_e32 v98, v113, v98
	v_add_f32_e32 v98, 0, v98
	v_cvt_pk_bf16_f32 v164, v110, v111
	v_cvt_pk_bf16_f32 v165, v112, v113
	s_add_i32 s7, s60, s91
	v_add_f32_e32 v202, v198, v98
	v_lshl_add_u64 v[98:99], v[146:147], 0, s[30:31]
	s_mov_b32 s12, m0
	s_mov_b32 m0, s7
	s_nop 0
	global_load_lds_dwordx4 v[98:99], off
	s_mov_b32 m0, s12
	s_lshl_b32 s7, s33, 14
	v_lshl_add_u64 v[106:107], v[148:149], 0, s[22:23]
	s_add_i32 s7, s7, s92
	s_mov_b32 s12, m0
	s_mov_b32 m0, s7
	s_nop 0
	global_load_lds_dwordx4 v[106:107], off
	s_mov_b32 m0, s12
	v_lshl_add_u64 v[98:99], v[148:149], 0, s[44:45]
	s_addk_i32 s7, 0x2000
	s_mov_b32 s12, m0
	s_mov_b32 m0, s7
	s_nop 0
	global_load_lds_dwordx4 v[98:99], off
	s_mov_b32 m0, s12
	s_waitcnt lgkmcnt(6)
	v_mfma_f32_32x32x16_bf16 v[50:65], v[174:177], v[194:197], v[50:65]
	v_exp_f32_e32 v82, v82
	v_exp_f32_e32 v83, v83
	ds_read_b64_tr_b16 v[98:99], v244 offset:25600
	ds_read_b64_tr_b16 v[100:101], v244 offset:26112
	s_waitcnt lgkmcnt(6)
	v_mfma_f32_32x32x16_bf16 v[34:49], v[174:177], v[114:117], v[34:49]
	v_exp_f32_e32 v84, v84
	v_exp_f32_e32 v85, v85
	ds_read_b64_tr_b16 v[102:103], v244 offset:29696
	ds_read_b64_tr_b16 v[104:105], v244 offset:30208
	s_waitcnt lgkmcnt(6)
	v_mfma_f32_32x32x16_bf16 v[18:33], v[174:177], v[118:121], v[18:33]
	v_exp_f32_e32 v86, v86
	v_exp_f32_e32 v87, v87
	ds_read_b64_tr_b16 v[108:109], v244 offset:33792
	ds_read_b64_tr_b16 v[110:111], v244 offset:34304
	s_waitcnt lgkmcnt(6)
	v_mfma_f32_32x32x16_bf16 v[2:17], v[174:177], v[122:125], v[2:17]
	v_exp_f32_e32 v88, v88
	v_exp_f32_e32 v89, v89
	ds_read_b64_tr_b16 v[112:113], v244 offset:37888
	ds_read_b64_tr_b16 v[114:115], v244 offset:38400
	s_waitcnt lgkmcnt(6)
	v_mfma_f32_32x32x16_bf16 v[50:65], v[170:173], v[98:101], v[50:65]
	v_exp_f32_e32 v90, v90
	v_exp_f32_e32 v91, v91
	ds_read_b64_tr_b16 v[116:117], v244 offset:26624
	ds_read_b64_tr_b16 v[118:119], v244 offset:27136
	s_waitcnt lgkmcnt(6)
	v_mfma_f32_32x32x16_bf16 v[34:49], v[170:173], v[102:105], v[34:49]
	v_exp_f32_e32 v92, v92
	v_exp_f32_e32 v93, v93
	ds_read_b64_tr_b16 v[120:121], v244 offset:30720
	ds_read_b64_tr_b16 v[122:123], v244 offset:31232
	s_waitcnt lgkmcnt(6)
	v_mfma_f32_32x32x16_bf16 v[18:33], v[170:173], v[108:111], v[18:33]
	v_exp_f32_e32 v94, v94
	v_exp_f32_e32 v95, v95
	v_lshl_add_u32 v128, s33, 13, v243
	ds_read_b128 v[102:105], v128
	ds_read_b128 v[98:101], v128 offset:512
	ds_read_b64_tr_b16 v[124:125], v244 offset:34816
	ds_read_b64_tr_b16 v[126:127], v244 offset:35328
	s_waitcnt lgkmcnt(8)
; #define ATT_WAIT_BAR(N) asm volatile("s_waitcnt vmcnt(" #N ") lgkmcnt(0)\n\ts_barrier" ::: "memory")
; #define ROT() do { sl_prev = sl_cur; sl_cur = sl_next; sl_next = (sl_next == 2) ? 0 : sl_next + 1; } while (0)
; __device__ __forceinline__ void attn_unit(int b, int h, int qb, bool first, bool has_next, int nb, int nh, bf16_t* QO, const bf16_t* __restrict__ K, const bf16_t* __restrict__ V, float lam, char* shm) {
;     ...
;         int t = 1;
; #pragma unroll 1
;         for (; t + 1 <= NT - 4; t += 2) {
;             STEP(pB0, pB1, pA0, pA1, t, true, true, true);     ATT_WAIT_BAR(3); ROT();
;             STEP(pA0, pA1, pB0, pB1, t + 1, true, true, true); ATT_WAIT_BAR(3); ROT();
;         }
;         STEP(pB0, pB1, pA0, pA1, NT - 3, false, true, true);   ATT_WAIT_BAR(2); ROT();
	v_mfma_f32_32x32x16_bf16 v[2:17], v[170:173], v[112:115], v[2:17]
	v_exp_f32_e32 v96, v96
	v_exp_f32_e32 v97, v97
	ds_read_b64_tr_b16 v[108:109], v244 offset:38912
	ds_read_b64_tr_b16 v[110:111], v244 offset:39424
	s_waitcnt lgkmcnt(8)
	v_mfma_f32_32x32x16_bf16 v[50:65], v[166:169], v[116:119], v[50:65]
	v_exp_f32_e32 v66, v66
	v_exp_f32_e32 v67, v67
	ds_read_b128 v[198:201], v128 offset:2048
	ds_read_b128 v[142:145], v128 offset:2560
	ds_read_b64_tr_b16 v[112:113], v244 offset:27648
	ds_read_b64_tr_b16 v[114:115], v244 offset:28160
	s_waitcnt lgkmcnt(10)
	v_mfma_f32_32x32x16_bf16 v[34:49], v[166:169], v[120:123], v[34:49]
	v_exp_f32_e32 v68, v68
	v_exp_f32_e32 v69, v69
	ds_read_b64_tr_b16 v[116:117], v244 offset:31744
	ds_read_b64_tr_b16 v[118:119], v244 offset:32256
	s_waitcnt lgkmcnt(8)
	v_mfma_f32_32x32x16_bf16 v[18:33], v[166:169], v[124:127], v[18:33]
	v_exp_f32_e32 v70, v70
	v_exp_f32_e32 v71, v71
	ds_read_b128 v[194:197], v128 offset:4096
	ds_read_b128 v[134:137], v128 offset:4608
	ds_read_b64_tr_b16 v[120:121], v244 offset:35840
	ds_read_b64_tr_b16 v[122:123], v244 offset:36352
	s_waitcnt lgkmcnt(10)
	v_mfma_f32_32x32x16_bf16 v[2:17], v[166:169], v[108:111], v[2:17]
	v_exp_f32_e32 v72, v72
	v_exp_f32_e32 v73, v73
	ds_read_b64_tr_b16 v[124:125], v244 offset:39936
	ds_read_b64_tr_b16 v[126:127], v244 offset:40448
	s_waitcnt lgkmcnt(8)
	v_mfma_f32_32x32x16_bf16 v[50:65], v[162:165], v[112:115], v[50:65]
	ds_read_b128 v[138:141], v128 offset:6144
	ds_read_b128 v[130:133], v128 offset:6656
	v_exp_f32_e32 v74, v74
	v_exp_f32_e32 v75, v75
	s_cmp_lg_u32 s98, 0
	s_cbranch_scc0 .Lst_e1
	s_waitcnt vmcnt(3) lgkmcnt(0)
	s_barrier
.Lst_e1:
	s_waitcnt lgkmcnt(8)
	v_mfma_f32_32x32x16_bf16 v[34:49], v[162:165], v[116:119], v[34:49]
	v_exp_f32_e32 v76, v76
	v_exp_f32_e32 v77, v77
	s_waitcnt lgkmcnt(4)
	v_mfma_f32_32x32x16_bf16 v[18:33], v[162:165], v[120:123], v[18:33]
	v_exp_f32_e32 v78, v78
	v_exp_f32_e32 v79, v79
	s_waitcnt lgkmcnt(2)
	v_mfma_f32_32x32x16_bf16 v[2:17], v[162:165], v[124:127], v[2:17]
	v_exp_f32_e32 v80, v80
	v_exp_f32_e32 v81, v81
	s_add_i32 s12, s33, 1
	s_waitcnt lgkmcnt(0)
	s_cmp_lg_u32 s33, 2
	s_mov_b32 s60, s0
	s_cselect_b32 s0, s12, 0
	s_add_i32 s6, s6, 2
	v_lshl_add_u64 v[146:147], v[146:147], 0, s[22:23]
	v_mov_b64_e32 v[148:149], v[106:107]
	s_mov_b32 s7, s33
	s_cmp_lt_u32 s6, 26
	s_cbranch_scc1 .LBB0_375
	s_cmp_lg_u32 s98, 0
	s_cbranch_scc1 .Lds_x0
	s_waitcnt vmcnt(3) lgkmcnt(0)
	s_barrier
.Lds_x0:
	ds_read_b64_tr_b16 v[106:107], v241 offset:40960
	ds_read_b64_tr_b16 v[108:109], v241 offset:41472
	v_add_f32_e32 v110, v82, v83
	v_add_f32_e32 v110, v84, v110
	v_add_f32_e32 v110, v85, v110
	v_add_f32_e32 v110, v86, v110
	v_add_f32_e32 v110, v87, v110
	v_cvt_pk_bf16_f32 v174, v82, v83
	v_cvt_pk_bf16_f32 v175, v84, v85
	v_mfma_f32_32x32x16_bf16 v[146:161], v[102:105], v[190:193], 0
	ds_read_b64_tr_b16 v[82:83], v241 offset:45056
	ds_read_b64_tr_b16 v[84:85], v241 offset:45568
	v_mfma_f32_32x32x16_bf16 v[114:129], v[98:101], v[190:193], 0
	v_add_f32_e32 v102, v88, v110
	v_add_f32_e32 v102, v89, v102
	v_add_f32_e32 v102, v90, v102
	v_add_f32_e32 v102, v91, v102
	v_cvt_pk_bf16_f32 v176, v86, v87
	v_cvt_pk_bf16_f32 v177, v88, v89
	ds_read_b64_tr_b16 v[86:87], v241 offset:49152
	ds_read_b64_tr_b16 v[88:89], v241 offset:49664
	v_add_f32_e32 v98, v92, v102
	v_add_f32_e32 v98, v93, v98
	v_add_f32_e32 v98, v94, v98
	v_add_f32_e32 v98, v95, v98
	v_cvt_pk_bf16_f32 v170, v90, v91
	v_cvt_pk_bf16_f32 v171, v92, v93
	v_mfma_f32_32x32x16_bf16 v[146:161], v[198:201], v[186:189], v[146:161]
	ds_read_b64_tr_b16 v[90:91], v241 offset:53248
	ds_read_b64_tr_b16 v[92:93], v241 offset:53760
	v_mfma_f32_32x32x16_bf16 v[114:129], v[142:145], v[186:189], v[114:129]
	v_add_f32_e32 v98, v96, v98
	v_add_f32_e32 v98, v97, v98
	v_add_f32_e32 v98, v66, v98
	v_add_f32_e32 v98, v67, v98
	v_cvt_pk_bf16_f32 v172, v94, v95
	v_cvt_pk_bf16_f32 v173, v96, v97
	s_nop 0
	v_add_f32_e32 v94, v68, v98
	v_add_f32_e32 v94, v69, v94
	v_add_f32_e32 v94, v70, v94
	v_add_f32_e32 v94, v71, v94
	v_cvt_pk_bf16_f32 v166, v66, v67
	v_cvt_pk_bf16_f32 v167, v68, v69
	v_mfma_f32_32x32x16_bf16 v[146:161], v[194:197], v[182:185], v[146:161]
	v_mfma_f32_32x32x16_bf16 v[114:129], v[134:137], v[182:185], v[114:129]
	v_add_f32_e32 v66, v72, v94
	v_add_f32_e32 v66, v73, v66
	v_add_f32_e32 v66, v74, v66
	v_add_f32_e32 v66, v75, v66
	v_cvt_pk_bf16_f32 v168, v70, v71
	v_cvt_pk_bf16_f32 v169, v72, v73
	s_nop 0
	v_add_f32_e32 v66, v76, v66
	v_add_f32_e32 v66, v77, v66
	v_add_f32_e32 v66, v78, v66
	v_add_f32_e32 v66, v79, v66
	v_cvt_pk_bf16_f32 v162, v74, v75
	v_cvt_pk_bf16_f32 v163, v76, v77
	s_waitcnt lgkmcnt(9)
	v_mfma_f32_32x32x16_bf16 v[146:161], v[138:141], v[178:181], v[146:161]
	s_waitcnt lgkmcnt(8)
	v_mfma_f32_32x32x16_bf16 v[114:129], v[130:133], v[178:181], v[114:129]
	v_add_f32_e32 v66, v80, v66
	v_add_f32_e32 v66, v81, v66
	v_add_f32_e32 v194, 0, v66
	v_cvt_pk_bf16_f32 v164, v78, v79
	v_cvt_pk_bf16_f32 v165, v80, v81
	s_mov_b32 s0, m0
	s_mov_b32 m0, s92
	s_nop 0
	global_load_lds_dwordx4 v[214:215], off
	s_mov_b32 m0, s0
	s_add_i32 s0, s92, 0x2000
	s_mov_b32 s6, m0
	s_mov_b32 m0, s0
	s_nop 0
	global_load_lds_dwordx4 v[216:217], off
	s_mov_b32 m0, s6
	s_waitcnt lgkmcnt(6)
	v_mfma_f32_32x32x16_bf16 v[50:65], v[174:177], v[106:109], v[50:65]
	s_nop 1
	v_exp_f32_e32 v146, v146
	v_exp_f32_e32 v147, v147
	ds_read_b64_tr_b16 v[66:67], v241 offset:41984
	ds_read_b64_tr_b16 v[68:69], v241 offset:42496
	s_waitcnt lgkmcnt(6)
	v_mfma_f32_32x32x16_bf16 v[34:49], v[174:177], v[82:85], v[34:49]
	v_exp_f32_e32 v148, v148
	v_exp_f32_e32 v149, v149
	ds_read_b64_tr_b16 v[70:71], v241 offset:46080
	ds_read_b64_tr_b16 v[72:73], v241 offset:46592
	s_waitcnt lgkmcnt(6)
; #define ATT_WAIT_BAR(N) asm volatile("s_waitcnt vmcnt(" #N ") lgkmcnt(0)\n\ts_barrier" ::: "memory")
; #define ROT() do { sl_prev = sl_cur; sl_cur = sl_next; sl_next = (sl_next == 2) ? 0 : sl_next + 1; } while (0)
; __device__ __forceinline__ void attn_unit(int b, int h, int qb, bool first, bool has_next, int nb, int nh, bf16_t* QO, const bf16_t* __restrict__ K, const bf16_t* __restrict__ V, float lam, char* shm) {
;     ...
;         int t = 1;
; #pragma unroll 1
;         for (; t + 1 <= NT - 4; t += 2) {
;             STEP(pB0, pB1, pA0, pA1, t, true, true, true);     ATT_WAIT_BAR(3); ROT();
;             STEP(pA0, pA1, pB0, pB1, t + 1, true, true, true); ATT_WAIT_BAR(3); ROT();
;         }
;         STEP(pB0, pB1, pA0, pA1, NT - 3, false, true, true);   ATT_WAIT_BAR(2); ROT();
;         STEP(pA0, pA1, pB0, pB1, NT - 2, false, true, true);   ATT_WAIT_BAR(0); ROT();
	v_mfma_f32_32x32x16_bf16 v[18:33], v[174:177], v[86:89], v[18:33]
	v_exp_f32_e32 v150, v150
	v_exp_f32_e32 v151, v151
	ds_read_b64_tr_b16 v[74:75], v241 offset:50176
	ds_read_b64_tr_b16 v[76:77], v241 offset:50688
	s_waitcnt lgkmcnt(6)
	v_mfma_f32_32x32x16_bf16 v[2:17], v[174:177], v[90:93], v[2:17]
	v_exp_f32_e32 v152, v152
	v_exp_f32_e32 v153, v153
	ds_read_b64_tr_b16 v[78:79], v241 offset:54272
	ds_read_b64_tr_b16 v[80:81], v241 offset:54784
	s_waitcnt lgkmcnt(6)
	v_mfma_f32_32x32x16_bf16 v[50:65], v[170:173], v[66:69], v[50:65]
	v_exp_f32_e32 v154, v154
	v_exp_f32_e32 v155, v155
	ds_read_b64_tr_b16 v[82:83], v241 offset:43008
	ds_read_b64_tr_b16 v[84:85], v241 offset:43520
	s_waitcnt lgkmcnt(6)
	v_mfma_f32_32x32x16_bf16 v[34:49], v[170:173], v[70:73], v[34:49]
	v_exp_f32_e32 v156, v156
	v_exp_f32_e32 v157, v157
	ds_read_b64_tr_b16 v[66:67], v241 offset:47104
	ds_read_b64_tr_b16 v[68:69], v241 offset:47616
	s_waitcnt lgkmcnt(6)
	v_mfma_f32_32x32x16_bf16 v[18:33], v[170:173], v[74:77], v[18:33]
	v_exp_f32_e32 v158, v158
	v_exp_f32_e32 v159, v159
	ds_read_b128 v[70:73], v243
	ds_read_b128 v[86:89], v243 offset:512
	ds_read_b64_tr_b16 v[90:91], v241 offset:51200
	ds_read_b64_tr_b16 v[92:93], v241 offset:51712
	s_waitcnt lgkmcnt(8)
	v_mfma_f32_32x32x16_bf16 v[2:17], v[170:173], v[78:81], v[2:17]
	v_exp_f32_e32 v160, v160
	v_exp_f32_e32 v161, v161
	ds_read_b64_tr_b16 v[74:75], v241 offset:55296
	ds_read_b64_tr_b16 v[76:77], v241 offset:55808
	s_waitcnt lgkmcnt(8)
	v_mfma_f32_32x32x16_bf16 v[50:65], v[166:169], v[82:85], v[50:65]
	v_exp_f32_e32 v114, v114
	v_exp_f32_e32 v115, v115
	ds_read_b128 v[78:81], v243 offset:2048
	ds_read_b128 v[94:97], v243 offset:2560
	ds_read_b64_tr_b16 v[98:99], v241 offset:44032
	ds_read_b64_tr_b16 v[100:101], v241 offset:44544
	s_waitcnt lgkmcnt(10)
	v_mfma_f32_32x32x16_bf16 v[34:49], v[166:169], v[66:69], v[34:49]
	v_exp_f32_e32 v116, v116
	v_exp_f32_e32 v117, v117
	ds_read_b64_tr_b16 v[82:83], v241 offset:48128
	ds_read_b64_tr_b16 v[84:85], v241 offset:48640
	s_waitcnt lgkmcnt(8)
	v_mfma_f32_32x32x16_bf16 v[18:33], v[166:169], v[90:93], v[18:33]
	v_exp_f32_e32 v118, v118
	v_exp_f32_e32 v119, v119
	ds_read_b128 v[66:69], v243 offset:4096
	ds_read_b128 v[196:199], v243 offset:4608
	ds_read_b64_tr_b16 v[102:103], v241 offset:52224
	ds_read_b64_tr_b16 v[104:105], v241 offset:52736
	s_waitcnt lgkmcnt(10)
	v_mfma_f32_32x32x16_bf16 v[2:17], v[166:169], v[74:77], v[2:17]
	v_exp_f32_e32 v120, v120
	v_exp_f32_e32 v121, v121
	ds_read_b64_tr_b16 v[90:91], v241 offset:56320
	ds_read_b64_tr_b16 v[92:93], v241 offset:56832
	s_waitcnt lgkmcnt(8)
	v_mfma_f32_32x32x16_bf16 v[50:65], v[162:165], v[98:101], v[50:65]
	ds_read_b128 v[74:77], v243 offset:6144
	ds_read_b128 v[244:247], v243 offset:6656
	v_exp_f32_e32 v122, v122
	v_exp_f32_e32 v123, v123
	s_waitcnt lgkmcnt(8)
	v_mfma_f32_32x32x16_bf16 v[34:49], v[162:165], v[82:85], v[34:49]
	v_exp_f32_e32 v124, v124
	v_exp_f32_e32 v125, v125
	s_waitcnt lgkmcnt(4)
	v_mfma_f32_32x32x16_bf16 v[18:33], v[162:165], v[102:105], v[18:33]
	v_exp_f32_e32 v126, v126
	v_exp_f32_e32 v127, v127
	s_waitcnt lgkmcnt(2)
	v_mfma_f32_32x32x16_bf16 v[2:17], v[162:165], v[90:93], v[2:17]
	v_exp_f32_e32 v128, v128
	v_exp_f32_e32 v129, v129
	s_waitcnt vmcnt(2) lgkmcnt(0)
	s_barrier
	ds_read_b64_tr_b16 v[82:83], v241 offset:57344
	ds_read_b64_tr_b16 v[84:85], v241 offset:57856
	v_add_f32_e32 v90, v146, v147
	v_add_f32_e32 v90, v148, v90
	v_add_f32_e32 v90, v149, v90
	v_add_f32_e32 v90, v150, v90
	v_add_f32_e32 v90, v151, v90
	v_cvt_pk_bf16_f32 v174, v146, v147
	v_cvt_pk_bf16_f32 v175, v148, v149
	v_mfma_f32_32x32x16_bf16 v[130:145], v[70:73], v[190:193], 0
	ds_read_b64_tr_b16 v[70:71], v241 offset:61440
	ds_read_b64_tr_b16 v[72:73], v241 offset:61952
	v_mfma_f32_32x32x16_bf16 v[98:113], v[86:89], v[190:193], 0
	v_add_f32_e32 v90, v152, v90
	v_add_f32_e32 v90, v153, v90
	v_add_f32_e32 v90, v154, v90
	v_add_f32_e32 v90, v155, v90
	v_cvt_pk_bf16_f32 v176, v150, v151
	v_cvt_pk_bf16_f32 v177, v152, v153
	ds_read_b64_tr_b16 v[86:87], v242 offset:40960
	ds_read_b64_tr_b16 v[88:89], v242 offset:41472
	v_add_f32_e32 v90, v156, v90
	v_add_f32_e32 v90, v157, v90
	v_add_f32_e32 v90, v158, v90
	v_add_f32_e32 v90, v159, v90
	v_cvt_pk_bf16_f32 v170, v154, v155
	v_cvt_pk_bf16_f32 v171, v156, v157
	v_mfma_f32_32x32x16_bf16 v[130:145], v[78:81], v[186:189], v[130:145]
	ds_read_b64_tr_b16 v[78:79], v242 offset:45056
	ds_read_b64_tr_b16 v[80:81], v242 offset:45568
	v_mfma_f32_32x32x16_bf16 v[98:113], v[94:97], v[186:189], v[98:113]
	v_add_f32_e32 v90, v160, v90
	v_add_f32_e32 v90, v161, v90
	v_add_f32_e32 v90, v114, v90
	v_add_f32_e32 v90, v115, v90
	v_cvt_pk_bf16_f32 v172, v158, v159
	v_cvt_pk_bf16_f32 v173, v160, v161
	s_nop 0
	v_add_f32_e32 v90, v116, v90
	v_add_f32_e32 v90, v117, v90
	v_add_f32_e32 v90, v118, v90
	v_add_f32_e32 v90, v119, v90
	v_cvt_pk_bf16_f32 v166, v114, v115
	v_cvt_pk_bf16_f32 v167, v116, v117
	v_mfma_f32_32x32x16_bf16 v[130:145], v[66:69], v[182:185], v[130:145]
	v_mfma_f32_32x32x16_bf16 v[98:113], v[196:199], v[182:185], v[98:113]
	v_add_f32_e32 v66, v120, v90
	v_add_f32_e32 v66, v121, v66
	v_add_f32_e32 v66, v122, v66
	v_add_f32_e32 v66, v123, v66
	v_cvt_pk_bf16_f32 v168, v118, v119
	v_cvt_pk_bf16_f32 v169, v120, v121
	s_nop 0
	v_add_f32_e32 v66, v124, v66
	v_add_f32_e32 v66, v125, v66
	v_add_f32_e32 v66, v126, v66
	v_add_f32_e32 v66, v127, v66
	v_cvt_pk_bf16_f32 v162, v122, v123
	v_cvt_pk_bf16_f32 v163, v124, v125
	s_waitcnt lgkmcnt(9)
	v_mfma_f32_32x32x16_bf16 v[130:145], v[74:77], v[178:181], v[130:145]
	s_waitcnt lgkmcnt(8)
; #define ATT_WAIT_BAR(N) asm volatile("s_waitcnt vmcnt(" #N ") lgkmcnt(0)\n\ts_barrier" ::: "memory")
; #define ROT() do { sl_prev = sl_cur; sl_cur = sl_next; sl_next = (sl_next == 2) ? 0 : sl_next + 1; } while (0)
; __device__ __forceinline__ void attn_unit(int b, int h, int qb, bool first, bool has_next, int nb, int nh, bf16_t* QO, const bf16_t* __restrict__ K, const bf16_t* __restrict__ V, float lam, char* shm) {
;     ...
;         int t = 1;
; #pragma unroll 1
;         for (; t + 1 <= NT - 4; t += 2) {
;             STEP(pB0, pB1, pA0, pA1, t, true, true, true);     ATT_WAIT_BAR(3); ROT();
;             STEP(pA0, pA1, pB0, pB1, t + 1, true, true, true); ATT_WAIT_BAR(3); ROT();
;         }
;         STEP(pB0, pB1, pA0, pA1, NT - 3, false, true, true);   ATT_WAIT_BAR(2); ROT();
;         STEP(pA0, pA1, pB0, pB1, NT - 2, false, true, true);   ATT_WAIT_BAR(0); ROT();
	v_mfma_f32_32x32x16_bf16 v[98:113], v[244:247], v[178:181], v[98:113]
	v_add_f32_e32 v66, v128, v66
	v_add_f32_e32 v66, v129, v66
	v_add_f32_e32 v114, 0, v66
	v_cvt_pk_bf16_f32 v164, v126, v127
	v_cvt_pk_bf16_f32 v165, v128, v129
	s_cmp_lg_u32 0, -1
	s_cselect_b32 s0, 0, 0
	s_add_i32 s0, s0, s90
	s_add_i32 s6, s0, 0xa000
	s_mov_b32 s7, m0
	s_mov_b32 m0, s6
	s_nop 0
	global_load_lds_dwordx4 v[218:219], off
	s_mov_b32 m0, s7
	s_add_i32 s0, s0, 0xc000
	s_mov_b32 s6, m0
	s_mov_b32 m0, s0
	s_nop 0
	global_load_lds_dwordx4 v[220:221], off
	s_mov_b32 m0, s6
	s_waitcnt lgkmcnt(6)
	v_mfma_f32_32x32x16_bf16 v[50:65], v[174:177], v[82:85], v[50:65]
	v_exp_f32_e32 v130, v130
	v_exp_f32_e32 v131, v131
	ds_read_b64_tr_b16 v[66:67], v241 offset:58368
	ds_read_b64_tr_b16 v[68:69], v241 offset:58880
	s_waitcnt lgkmcnt(6)
	v_mfma_f32_32x32x16_bf16 v[34:49], v[174:177], v[70:73], v[34:49]
	v_exp_f32_e32 v132, v132
	v_exp_f32_e32 v133, v133
	ds_read_b64_tr_b16 v[74:75], v241 offset:62464
	ds_read_b64_tr_b16 v[76:77], v241 offset:62976
	s_waitcnt lgkmcnt(6)
	v_mfma_f32_32x32x16_bf16 v[18:33], v[174:177], v[86:89], v[18:33]
	v_exp_f32_e32 v134, v134
	v_exp_f32_e32 v135, v135
	ds_read_b64_tr_b16 v[70:71], v242 offset:41984
	ds_read_b64_tr_b16 v[72:73], v242 offset:42496
	s_waitcnt lgkmcnt(6)
	v_mfma_f32_32x32x16_bf16 v[2:17], v[174:177], v[78:81], v[2:17]
	v_exp_f32_e32 v136, v136
	v_exp_f32_e32 v137, v137
	ds_read_b64_tr_b16 v[82:83], v242 offset:46080
	ds_read_b64_tr_b16 v[84:85], v242 offset:46592
	s_waitcnt lgkmcnt(6)
	v_mfma_f32_32x32x16_bf16 v[50:65], v[170:173], v[66:69], v[50:65]
	v_exp_f32_e32 v138, v138
	v_exp_f32_e32 v139, v139
	ds_read_b64_tr_b16 v[78:79], v241 offset:59392
	ds_read_b64_tr_b16 v[80:81], v241 offset:59904
	s_waitcnt lgkmcnt(6)
	v_mfma_f32_32x32x16_bf16 v[34:49], v[170:173], v[74:77], v[34:49]
	v_exp_f32_e32 v140, v140
	v_exp_f32_e32 v141, v141
	ds_read_b64_tr_b16 v[66:67], v241 offset:63488
	ds_read_b64_tr_b16 v[68:69], v241 offset:64000
	s_waitcnt lgkmcnt(6)
	v_mfma_f32_32x32x16_bf16 v[18:33], v[170:173], v[70:73], v[18:33]
	v_exp_f32_e32 v142, v142
	v_exp_f32_e32 v143, v143
	ds_read_b128 v[74:77], v243 offset:8192
	ds_read_b128 v[86:89], v243 offset:8704
	ds_read_b64_tr_b16 v[90:91], v242 offset:43008
	ds_read_b64_tr_b16 v[92:93], v242 offset:43520
	s_waitcnt lgkmcnt(8)
	v_mfma_f32_32x32x16_bf16 v[2:17], v[170:173], v[82:85], v[2:17]
	v_exp_f32_e32 v144, v144
	v_exp_f32_e32 v145, v145
	ds_read_b64_tr_b16 v[70:71], v242 offset:47104
	ds_read_b64_tr_b16 v[72:73], v242 offset:47616
	s_waitcnt lgkmcnt(8)
	v_mfma_f32_32x32x16_bf16 v[50:65], v[166:169], v[78:81], v[50:65]
	v_exp_f32_e32 v98, v98
	v_exp_f32_e32 v99, v99
	ds_read_b128 v[116:119], v243 offset:10240
	ds_read_b128 v[120:123], v243 offset:10752
	ds_read_b64_tr_b16 v[82:83], v241 offset:60416
	ds_read_b64_tr_b16 v[84:85], v241 offset:60928
	s_waitcnt lgkmcnt(10)
	v_mfma_f32_32x32x16_bf16 v[34:49], v[166:169], v[66:69], v[34:49]
	v_exp_f32_e32 v100, v100
	v_exp_f32_e32 v101, v101
	ds_read_b64_tr_b16 v[78:79], v241 offset:64512
	ds_read_b64_tr_b16 v[80:81], v241 offset:65024
	s_waitcnt lgkmcnt(8)
	v_mfma_f32_32x32x16_bf16 v[18:33], v[166:169], v[90:93], v[18:33]
	v_exp_f32_e32 v102, v102
	v_exp_f32_e32 v103, v103
	ds_read_b128 v[124:127], v243 offset:12288
	ds_read_b128 v[146:149], v243 offset:12800
	ds_read_b64_tr_b16 v[66:67], v242 offset:44032
	ds_read_b64_tr_b16 v[68:69], v242 offset:44544
	s_waitcnt lgkmcnt(10)
	v_mfma_f32_32x32x16_bf16 v[2:17], v[166:169], v[70:73], v[2:17]
	v_exp_f32_e32 v104, v104
	v_exp_f32_e32 v105, v105
	ds_read_b64_tr_b16 v[90:91], v242 offset:48128
	ds_read_b64_tr_b16 v[92:93], v242 offset:48640
	s_waitcnt lgkmcnt(8)
	v_mfma_f32_32x32x16_bf16 v[50:65], v[162:165], v[82:85], v[50:65]
	ds_read_b128 v[150:153], v243 offset:14336
	ds_read_b128 v[154:157], v243 offset:14848
	v_exp_f32_e32 v106, v106
	v_exp_f32_e32 v107, v107
	s_waitcnt lgkmcnt(8)
	v_mfma_f32_32x32x16_bf16 v[34:49], v[162:165], v[78:81], v[34:49]
	v_exp_f32_e32 v108, v108
	v_exp_f32_e32 v109, v109
	s_waitcnt lgkmcnt(4)
	v_mfma_f32_32x32x16_bf16 v[18:33], v[162:165], v[66:69], v[18:33]
	v_exp_f32_e32 v110, v110
	v_exp_f32_e32 v111, v111
	s_waitcnt lgkmcnt(2)
	v_mfma_f32_32x32x16_bf16 v[2:17], v[162:165], v[90:93], v[2:17]
	v_exp_f32_e32 v112, v112
	v_exp_f32_e32 v113, v113
	s_waitcnt vmcnt(0) lgkmcnt(0)
	s_barrier
; #define ATT_WAIT_BAR(N) asm volatile("s_waitcnt vmcnt(" #N ") lgkmcnt(0)\n\ts_barrier" ::: "memory")
; #define ROT() do { sl_prev = sl_cur; sl_cur = sl_next; sl_next = (sl_next == 2) ? 0 : sl_next + 1; } while (0)
; __device__ __forceinline__ void attn_unit(int b, int h, int qb, bool first, bool has_next, int nb, int nh, bf16_t* QO, const bf16_t* __restrict__ K, const bf16_t* __restrict__ V, float lam, char* shm) {
;     ...
;         int t = 1;
; #pragma unroll 1
;         for (; t + 1 <= NT - 4; t += 2) {
;             STEP(pB0, pB1, pA0, pA1, t, true, true, true);     ATT_WAIT_BAR(3); ROT();
;             STEP(pA0, pA1, pB0, pB1, t + 1, true, true, true); ATT_WAIT_BAR(3); ROT();
;         }
;         STEP(pB0, pB1, pA0, pA1, NT - 3, false, true, true);   ATT_WAIT_BAR(2); ROT();
;         STEP(pA0, pA1, pB0, pB1, NT - 2, false, true, true);   ATT_WAIT_BAR(0); ROT();
;         STEP(pB0, pB1, pA0, pA1, NT - 1, false, false, false);
	ds_read_b64_tr_b16 v[158:159], v241 offset:24576
	ds_read_b64_tr_b16 v[160:161], v241 offset:25088
	v_add_f32_e32 v66, v130, v131
	v_add_f32_e32 v66, v132, v66
	v_add_f32_e32 v66, v133, v66
	v_add_f32_e32 v66, v134, v66
	v_add_f32_e32 v82, v135, v66
	v_mfma_f32_32x32x16_bf16 v[66:81], v[74:77], v[190:193], 0
	v_cvt_pk_bf16_f32 v174, v130, v131
	v_cvt_pk_bf16_f32 v175, v132, v133
	ds_read_b64_tr_b16 v[128:129], v241 offset:28672
	ds_read_b64_tr_b16 v[130:131], v241 offset:29184
	v_add_f32_e32 v82, v136, v82
	v_add_f32_e32 v82, v137, v82
	v_add_f32_e32 v82, v138, v82
	v_add_f32_e32 v115, v139, v82
	v_mfma_f32_32x32x16_bf16 v[82:97], v[86:89], v[190:193], 0
	v_cvt_pk_bf16_f32 v176, v134, v135
	v_cvt_pk_bf16_f32 v177, v136, v137
	ds_read_b64_tr_b16 v[132:133], v241 offset:32768
	ds_read_b64_tr_b16 v[134:135], v241 offset:33280
	v_mfma_f32_32x32x16_bf16 v[66:81], v[116:119], v[186:189], v[66:81]
	v_add_f32_e32 v115, v140, v115
	v_add_f32_e32 v115, v141, v115
	v_add_f32_e32 v115, v142, v115
	v_add_f32_e32 v115, v143, v115
	v_cvt_pk_bf16_f32 v170, v138, v139
	v_cvt_pk_bf16_f32 v171, v140, v141
	ds_read_b64_tr_b16 v[116:117], v241 offset:36864
	ds_read_b64_tr_b16 v[118:119], v241 offset:37376
	v_mfma_f32_32x32x16_bf16 v[82:97], v[120:123], v[186:189], v[82:97]
	v_add_f32_e32 v115, v144, v115
	v_add_f32_e32 v115, v145, v115
	v_add_f32_e32 v115, v98, v115
	v_add_f32_e32 v115, v99, v115
	v_cvt_pk_bf16_f32 v172, v142, v143
	v_cvt_pk_bf16_f32 v173, v144, v145
	v_mfma_f32_32x32x16_bf16 v[66:81], v[124:127], v[182:185], v[66:81]
	v_add_f32_e32 v115, v100, v115
	v_add_f32_e32 v115, v101, v115
	v_add_f32_e32 v115, v102, v115
	v_add_f32_e32 v115, v103, v115
	v_cvt_pk_bf16_f32 v166, v98, v99
	v_cvt_pk_bf16_f32 v167, v100, v101
	v_mfma_f32_32x32x16_bf16 v[82:97], v[146:149], v[182:185], v[82:97]
	v_add_f32_e32 v98, v104, v115
	v_add_f32_e32 v98, v105, v98
	v_add_f32_e32 v98, v106, v98
	v_add_f32_e32 v98, v107, v98
	v_cvt_pk_bf16_f32 v168, v102, v103
	v_cvt_pk_bf16_f32 v169, v104, v105
	s_waitcnt lgkmcnt(9)
	v_mfma_f32_32x32x16_bf16 v[66:81], v[150:153], v[178:181], v[66:81]
	v_add_f32_e32 v98, v108, v98
	v_add_f32_e32 v98, v109, v98
	v_add_f32_e32 v98, v110, v98
	v_add_f32_e32 v98, v111, v98
	v_cvt_pk_bf16_f32 v162, v106, v107
	v_cvt_pk_bf16_f32 v163, v108, v109
	s_waitcnt lgkmcnt(8)
	v_mfma_f32_32x32x16_bf16 v[82:97], v[154:157], v[178:181], v[82:97]
	v_add_f32_e32 v98, v112, v98
	v_add_f32_e32 v98, v113, v98
	v_add_f32_e32 v98, 0, v98
	v_cvt_pk_bf16_f32 v164, v110, v111
	v_cvt_pk_bf16_f32 v165, v112, v113
	s_waitcnt lgkmcnt(6)
	v_mfma_f32_32x32x16_bf16 v[50:65], v[174:177], v[158:161], v[50:65]
	v_exp_f32_e32 v66, v66
	v_exp_f32_e32 v67, v67
	ds_read_b64_tr_b16 v[100:101], v241 offset:25600
	ds_read_b64_tr_b16 v[102:103], v241 offset:26112
	s_waitcnt lgkmcnt(6)
	v_mfma_f32_32x32x16_bf16 v[34:49], v[174:177], v[128:131], v[34:49]
	v_exp_f32_e32 v68, v68
	v_exp_f32_e32 v69, v69
	ds_read_b64_tr_b16 v[104:105], v241 offset:29696
	ds_read_b64_tr_b16 v[106:107], v241 offset:30208
	s_waitcnt lgkmcnt(6)
	v_mfma_f32_32x32x16_bf16 v[18:33], v[174:177], v[132:135], v[18:33]
	v_exp_f32_e32 v70, v70
	v_exp_f32_e32 v71, v71
	ds_read_b64_tr_b16 v[108:109], v241 offset:33792
	ds_read_b64_tr_b16 v[110:111], v241 offset:34304
	s_waitcnt lgkmcnt(6)
	v_mfma_f32_32x32x16_bf16 v[2:17], v[174:177], v[116:119], v[2:17]
	v_exp_f32_e32 v72, v72
	v_exp_f32_e32 v73, v73
	ds_read_b64_tr_b16 v[120:121], v241 offset:37888
	ds_read_b64_tr_b16 v[122:123], v241 offset:38400
	s_waitcnt lgkmcnt(6)
	v_mfma_f32_32x32x16_bf16 v[50:65], v[170:173], v[100:103], v[50:65]
	v_exp_f32_e32 v74, v74
	v_exp_f32_e32 v75, v75
	ds_read_b64_tr_b16 v[116:117], v241 offset:26624
	ds_read_b64_tr_b16 v[118:119], v241 offset:27136
	s_waitcnt lgkmcnt(6)
	v_mfma_f32_32x32x16_bf16 v[34:49], v[170:173], v[104:107], v[34:49]
	v_exp_f32_e32 v76, v76
	v_exp_f32_e32 v77, v77
	ds_read_b64_tr_b16 v[100:101], v241 offset:30720
	ds_read_b64_tr_b16 v[102:103], v241 offset:31232
	s_waitcnt lgkmcnt(6)
	v_mfma_f32_32x32x16_bf16 v[18:33], v[170:173], v[108:111], v[18:33]
	v_exp_f32_e32 v78, v78
	v_exp_f32_e32 v79, v79
	ds_read_b64_tr_b16 v[104:105], v241 offset:34816
	ds_read_b64_tr_b16 v[106:107], v241 offset:35328
	s_waitcnt lgkmcnt(6)
	v_mfma_f32_32x32x16_bf16 v[2:17], v[170:173], v[120:123], v[2:17]
	v_exp_f32_e32 v80, v80
	v_exp_f32_e32 v81, v81
	ds_read_b64_tr_b16 v[108:109], v241 offset:38912
	ds_read_b64_tr_b16 v[110:111], v241 offset:39424
	s_waitcnt lgkmcnt(6)
	v_mfma_f32_32x32x16_bf16 v[50:65], v[166:169], v[116:119], v[50:65]
	v_exp_f32_e32 v82, v82
	v_exp_f32_e32 v83, v83
	ds_read_b64_tr_b16 v[120:121], v241 offset:27648
	ds_read_b64_tr_b16 v[122:123], v241 offset:28160
	s_waitcnt lgkmcnt(6)
	v_mfma_f32_32x32x16_bf16 v[34:49], v[166:169], v[100:103], v[34:49]
	v_exp_f32_e32 v84, v84
	v_exp_f32_e32 v85, v85
	ds_read_b64_tr_b16 v[116:117], v241 offset:31744
	ds_read_b64_tr_b16 v[118:119], v241 offset:32256
	s_waitcnt lgkmcnt(6)
	v_mfma_f32_32x32x16_bf16 v[18:33], v[166:169], v[104:107], v[18:33]
	v_exp_f32_e32 v86, v86
	v_exp_f32_e32 v87, v87
	ds_read_b64_tr_b16 v[100:101], v241 offset:35840
	ds_read_b64_tr_b16 v[102:103], v241 offset:36352
	s_waitcnt lgkmcnt(6)
	v_mfma_f32_32x32x16_bf16 v[2:17], v[166:169], v[108:111], v[2:17]
	v_exp_f32_e32 v88, v88
	v_exp_f32_e32 v89, v89
	ds_read_b64_tr_b16 v[104:105], v241 offset:39936
	ds_read_b64_tr_b16 v[106:107], v241 offset:40448
	s_waitcnt lgkmcnt(6)
; __device__ __forceinline__ s16x4 vtr(lds_cptr p) { return __builtin_bit_cast(s16x4, __builtin_amdgcn_ds_read_tr16_b64_v4i16((LAS v4i16_t*)p)); }
; __device__ __forceinline__ void attn_unit(int b, int h, int qb, bool first, bool has_next, int nb, int nh, bf16_t* QO, const bf16_t* __restrict__ K, const bf16_t* __restrict__ V, float lam, char* shm) {
;     ...
;         { float sacc = pB0[0] + pB0[1];
; #pragma unroll
;           for (int r = 2; r < 16; ++r) sacc += pB0[r];
; #pragma unroll
;           for (int r = 0; r < 16; ++r) sacc += pB1[r];
;           l_reg += sacc;
;           pw0 = (u32x4){ATT_PK(pB0[0], pB0[1]), ATT_PK(pB0[2], pB0[3]), ATT_PK(pB0[4], pB0[5]), ATT_PK(pB0[6], pB0[7])};
;           pw1 = (u32x4){ATT_PK(pB0[8], pB0[9]), ATT_PK(pB0[10], pB0[11]), ATT_PK(pB0[12], pB0[13]), ATT_PK(pB0[14], pB0[15])};
;           pw2 = (u32x4){ATT_PK(pB1[0], pB1[1]), ATT_PK(pB1[2], pB1[3]), ATT_PK(pB1[4], pB1[5]), ATT_PK(pB1[6], pB1[7])};
;           pw3 = (u32x4){ATT_PK(pB1[8], pB1[9]), ATT_PK(pB1[10], pB1[11]), ATT_PK(pB1[12], pB1[13]), ATT_PK(pB1[14], pB1[15])};
;           ATT_SB();
;           const lds_cptr vp = vp0 + sl_cur * VSLOT;
; #pragma unroll
;           for (int d0 = 0; d0 < 4; ++d0) {
;               const s16x4 l0 = vtr(vp + d0 * 4096), h0 = vtr(vp + d0 * 4096 + 512), l1 = vtr(vp + d0 * 4096 + 1024), h1 = vtr(vp + d0 * 4096 + 1536);
;               const s16x4 l2 = vtr(vp + d0 * 4096 + 2048), h2 = vtr(vp + d0 * 4096 + 2560), l3 = vtr(vp + d0 * 4096 + 3072), h3 = vtr(vp + d0 * 4096 + 3584);
;               o[d0] = ATT_MFMA(PAF(0), ((bf16x8){l0[0], l0[1], l0[2], l0[3], h0[0], h0[1], h0[2], h0[3]}), o[d0]);
;               o[d0] = ATT_MFMA(PAF(1), ((bf16x8){l1[0], l1[1], l1[2], l1[3], h1[0], h1[1], h1[2], h1[3]}), o[d0]);
;               o[d0] = ATT_MFMA(PAF(2), ((bf16x8){l2[0], l2[1], l2[2], l2[3], h2[0], h2[1], h2[2], h2[3]}), o[d0]);
;               o[d0] = ATT_MFMA(PAF(3), ((bf16x8){l3[0], l3[1], l3[2], l3[3], h3[0], h3[1], h3[2], h3[3]}), o[d0]); } }
;     ...
;         ATT_SB();
;         asm volatile("s_waitcnt lgkmcnt(0)\n\ts_barrier" ::: "memory");
;         ATT_SB();
;         if (map == 0 || has_next) {
;             const bf16_t* nk = (map == 0) ? ksrc + 1024 : K + (long)nb * SEQ * DM + (2 * nh) * 1024 + klane;
;             const bf16_t* nv = (map == 0) ? vsrc0 : V + (long)nb * SEQ * DM + nh * 2048 + vlane;
	v_mfma_f32_32x32x16_bf16 v[50:65], v[162:165], v[120:123], v[50:65]
	v_exp_f32_e32 v90, v90
	v_exp_f32_e32 v91, v91
	s_waitcnt lgkmcnt(4)
	v_mfma_f32_32x32x16_bf16 v[34:49], v[162:165], v[116:119], v[34:49]
	v_exp_f32_e32 v92, v92
	v_exp_f32_e32 v93, v93
	s_waitcnt lgkmcnt(2)
	v_mfma_f32_32x32x16_bf16 v[18:33], v[162:165], v[100:103], v[18:33]
	v_exp_f32_e32 v94, v94
	v_exp_f32_e32 v95, v95
	s_waitcnt lgkmcnt(0)
	v_mfma_f32_32x32x16_bf16 v[2:17], v[162:165], v[104:107], v[2:17]
	v_exp_f32_e32 v96, v96
	v_exp_f32_e32 v97, v97
	v_cvt_pk_bf16_f32 v176, v70, v71
	v_cvt_pk_bf16_f32 v177, v72, v73
	v_cvt_pk_bf16_f32 v172, v78, v79
	v_cvt_pk_bf16_f32 v173, v80, v81
	v_cvt_pk_bf16_f32 v168, v86, v87
	v_cvt_pk_bf16_f32 v169, v88, v89
	v_cvt_pk_bf16_f32 v164, v94, v95
	v_cvt_pk_bf16_f32 v165, v96, v97
	v_cvt_pk_bf16_f32 v174, v66, v67
	v_cvt_pk_bf16_f32 v175, v68, v69
	v_cvt_pk_bf16_f32 v170, v74, v75
	v_cvt_pk_bf16_f32 v171, v76, v77
	v_cvt_pk_bf16_f32 v166, v82, v83
	v_cvt_pk_bf16_f32 v167, v84, v85
	v_cvt_pk_bf16_f32 v162, v90, v91
	v_cvt_pk_bf16_f32 v163, v92, v93
	ds_read_b64_tr_b16 v[100:101], v241 offset:40960
	ds_read_b64_tr_b16 v[102:103], v241 offset:41472
	ds_read_b64_tr_b16 v[104:105], v241 offset:41984
	ds_read_b64_tr_b16 v[106:107], v241 offset:42496
	s_waitcnt lgkmcnt(2)
	v_mfma_f32_32x32x16_bf16 v[50:65], v[174:177], v[100:103], v[50:65]
	s_waitcnt lgkmcnt(0)
	v_mfma_f32_32x32x16_bf16 v[50:65], v[170:173], v[104:107], v[50:65]
	ds_read_b64_tr_b16 v[100:101], v241 offset:43008
	ds_read_b64_tr_b16 v[102:103], v241 offset:43520
	ds_read_b64_tr_b16 v[104:105], v241 offset:44032
	ds_read_b64_tr_b16 v[106:107], v241 offset:44544
	s_waitcnt lgkmcnt(2)
	v_mfma_f32_32x32x16_bf16 v[50:65], v[166:169], v[100:103], v[50:65]
	s_waitcnt lgkmcnt(0)
	v_mfma_f32_32x32x16_bf16 v[50:65], v[162:165], v[104:107], v[50:65]
	ds_read_b64_tr_b16 v[100:101], v241 offset:45056
	ds_read_b64_tr_b16 v[102:103], v241 offset:45568
	ds_read_b64_tr_b16 v[104:105], v241 offset:46080
	ds_read_b64_tr_b16 v[106:107], v241 offset:46592
	s_waitcnt lgkmcnt(2)
	v_mfma_f32_32x32x16_bf16 v[34:49], v[174:177], v[100:103], v[34:49]
	s_waitcnt lgkmcnt(0)
	v_mfma_f32_32x32x16_bf16 v[34:49], v[170:173], v[104:107], v[34:49]
	ds_read_b64_tr_b16 v[100:101], v241 offset:47104
	ds_read_b64_tr_b16 v[102:103], v241 offset:47616
	ds_read_b64_tr_b16 v[104:105], v241 offset:48128
	ds_read_b64_tr_b16 v[106:107], v241 offset:48640
	s_waitcnt lgkmcnt(2)
	v_mfma_f32_32x32x16_bf16 v[34:49], v[166:169], v[100:103], v[34:49]
	s_waitcnt lgkmcnt(0)
	v_mfma_f32_32x32x16_bf16 v[34:49], v[162:165], v[104:107], v[34:49]
	ds_read_b64_tr_b16 v[100:101], v241 offset:49152
	ds_read_b64_tr_b16 v[102:103], v241 offset:49664
	ds_read_b64_tr_b16 v[104:105], v241 offset:50176
	ds_read_b64_tr_b16 v[106:107], v241 offset:50688
	s_waitcnt lgkmcnt(2)
	v_mfma_f32_32x32x16_bf16 v[18:33], v[174:177], v[100:103], v[18:33]
	s_waitcnt lgkmcnt(0)
	v_mfma_f32_32x32x16_bf16 v[18:33], v[170:173], v[104:107], v[18:33]
	ds_read_b64_tr_b16 v[100:101], v241 offset:51200
	ds_read_b64_tr_b16 v[102:103], v241 offset:51712
	ds_read_b64_tr_b16 v[104:105], v241 offset:52224
	ds_read_b64_tr_b16 v[106:107], v241 offset:52736
	s_waitcnt lgkmcnt(2)
	v_mfma_f32_32x32x16_bf16 v[18:33], v[166:169], v[100:103], v[18:33]
	s_waitcnt lgkmcnt(0)
	v_mfma_f32_32x32x16_bf16 v[18:33], v[162:165], v[104:107], v[18:33]
	ds_read_b64_tr_b16 v[100:101], v241 offset:53248
	ds_read_b64_tr_b16 v[102:103], v241 offset:53760
	ds_read_b64_tr_b16 v[104:105], v241 offset:54272
	ds_read_b64_tr_b16 v[106:107], v241 offset:54784
	s_waitcnt lgkmcnt(2)
	v_mfma_f32_32x32x16_bf16 v[2:17], v[174:177], v[100:103], v[2:17]
	s_waitcnt lgkmcnt(0)
	v_mfma_f32_32x32x16_bf16 v[2:17], v[170:173], v[104:107], v[2:17]
	ds_read_b64_tr_b16 v[100:101], v241 offset:55296
	ds_read_b64_tr_b16 v[102:103], v241 offset:55808
	ds_read_b64_tr_b16 v[104:105], v241 offset:56320
	ds_read_b64_tr_b16 v[106:107], v241 offset:56832
	s_waitcnt lgkmcnt(2)
	v_mfma_f32_32x32x16_bf16 v[2:17], v[166:169], v[100:103], v[2:17]
	s_waitcnt lgkmcnt(0)
	v_mfma_f32_32x32x16_bf16 v[2:17], v[162:165], v[104:107], v[2:17]
	s_waitcnt lgkmcnt(0)
	s_barrier
	s_or_b64 s[6:7], s[48:49], s[54:55]
	s_andn2_b64 vcc, exec, s[6:7]
	s_cbranch_vccnz .LBB0_378
	v_lshl_add_u64 v[100:101], v[232:233], 0, s[2:3]
	v_cndmask_b32_e64 v101, v223, v101, s[54:55]
	v_cndmask_b32_e64 v100, v222, v100, s[54:55]
	s_mov_b32 s0, m0
	s_mov_b32 m0, s91
	s_nop 0
	global_load_lds_dwordx4 v[100:101], off
	s_mov_b32 m0, s0
	v_cndmask_b32_e64 v103, v225, v205, s[54:55]
	v_cndmask_b32_e64 v102, v224, v204, s[54:55]
	s_mov_b32 s0, m0
	s_mov_b32 m0, s92
	s_nop 0
	global_load_lds_dwordx4 v[102:103], off
	s_mov_b32 m0, s0
	s_cmp_lg_u32 0, -1
	s_cselect_b32 s0, 0, 0
	s_add_i32 s0, s0, s90
	v_lshl_add_u64 v[102:103], v[102:103], 0, s[2:3]
	s_add_i32 s6, s0, 0x8000
	s_mov_b32 s7, m0
	s_mov_b32 m0, s6
	s_nop 0
	global_load_lds_dwordx4 v[102:103], off
	s_mov_b32 m0, s7
	v_lshl_add_u64 v[102:103], v[100:101], 0, s[4:5]
	s_add_i32 s6, s0, 0x2000
	s_mov_b32 s7, m0
	s_mov_b32 m0, s6
	s_nop 0
	global_load_lds_dwordx4 v[102:103], off
	s_mov_b32 m0, s7
	v_lshl_add_u64 v[100:101], v[100:101], 0, s[22:23]
	s_addk_i32 s0, 0x4000
	s_mov_b32 s6, m0
	s_mov_b32 m0, s0
	s_nop 0
	global_load_lds_dwordx4 v[100:101], off
	s_mov_b32 m0, s6
